# fp8 GEMM k-loops: one workgroup barrier per phase (waves 0-3 pre-MMA, waves 4-7 post-MMA) plus MFMAs reordered so 4 consecutive MFMAs share the weight fragment operand
# speedup vs baseline: 1.0019x; 1.0012x over previous
.Lhb_p5_0:
	s_setprio 1
	s_waitcnt lgkmcnt(0)
	v_mfma_scale_f32_16x16x128_f8f6f4 v[150:153], v[2:9], v[170:177], v[150:153], v182, v182 op_sel_hi:[0,0,0]
	v_mfma_scale_f32_16x16x128_f8f6f4 v[142:145], v[2:9], v[192:199], v[142:145], v182, v182 op_sel_hi:[0,0,0]
	v_mfma_scale_f32_16x16x128_f8f6f4 v[134:137], v[2:9], v[200:207], v[134:137], v182, v182 op_sel_hi:[0,0,0]
	v_mfma_scale_f32_16x16x128_f8f6f4 v[126:129], v[2:9], v[208:215], v[126:129], v182, v182 op_sel_hi:[0,0,0]
	v_mfma_scale_f32_16x16x128_f8f6f4 v[146:149], v[10:17], v[170:177], v[146:149], v182, v182 op_sel_hi:[0,0,0]
	v_mfma_scale_f32_16x16x128_f8f6f4 v[138:141], v[10:17], v[192:199], v[138:141], v182, v182 op_sel_hi:[0,0,0]
	v_mfma_scale_f32_16x16x128_f8f6f4 v[130:133], v[10:17], v[200:207], v[130:133], v182, v182 op_sel_hi:[0,0,0]
	v_mfma_scale_f32_16x16x128_f8f6f4 v[122:125], v[10:17], v[208:215], v[122:125], v182, v182 op_sel_hi:[0,0,0]
	s_setprio 0
	s_setprio 1
	v_mfma_scale_f32_16x16x128_f8f6f4 v[118:121], v[18:25], v[170:177], v[118:121], v182, v182 op_sel_hi:[0,0,0]
	v_mfma_scale_f32_16x16x128_f8f6f4 v[110:113], v[18:25], v[192:199], v[110:113], v182, v182 op_sel_hi:[0,0,0]
	v_mfma_scale_f32_16x16x128_f8f6f4 v[102:105], v[18:25], v[200:207], v[102:105], v182, v182 op_sel_hi:[0,0,0]
	v_mfma_scale_f32_16x16x128_f8f6f4 v[94:97], v[18:25], v[208:215], v[94:97], v182, v182 op_sel_hi:[0,0,0]
	v_mfma_scale_f32_16x16x128_f8f6f4 v[114:117], v[184:191], v[170:177], v[114:117], v182, v182 op_sel_hi:[0,0,0]
	v_mfma_scale_f32_16x16x128_f8f6f4 v[106:109], v[184:191], v[192:199], v[106:109], v182, v182 op_sel_hi:[0,0,0]
	v_mfma_scale_f32_16x16x128_f8f6f4 v[98:101], v[184:191], v[200:207], v[98:101], v182, v182 op_sel_hi:[0,0,0]
	v_mfma_scale_f32_16x16x128_f8f6f4 v[90:93], v[184:191], v[208:215], v[90:93], v182, v182 op_sel_hi:[0,0,0]
	s_setprio 0
	s_cmp_lg_u32 s98, 1
	s_cbranch_scc1 .Lhb_p5_1
	s_barrier

.Lhb_p5_2:
	s_setprio 1
	s_waitcnt lgkmcnt(0)
	v_mfma_scale_f32_16x16x128_f8f6f4 v[86:89], v[2:9], v[192:199], v[86:89], v182, v182 op_sel_hi:[0,0,0]
	v_mfma_scale_f32_16x16x128_f8f6f4 v[78:81], v[2:9], v[200:207], v[78:81], v182, v182 op_sel_hi:[0,0,0]
	v_mfma_scale_f32_16x16x128_f8f6f4 v[70:73], v[2:9], v[208:215], v[70:73], v182, v182 op_sel_hi:[0,0,0]
	v_mfma_scale_f32_16x16x128_f8f6f4 v[62:65], v[2:9], v[216:223], v[62:65], v182, v182 op_sel_hi:[0,0,0]
	v_mfma_scale_f32_16x16x128_f8f6f4 v[82:85], v[10:17], v[192:199], v[82:85], v182, v182 op_sel_hi:[0,0,0]
	v_mfma_scale_f32_16x16x128_f8f6f4 v[74:77], v[10:17], v[200:207], v[74:77], v182, v182 op_sel_hi:[0,0,0]
	v_mfma_scale_f32_16x16x128_f8f6f4 v[66:69], v[10:17], v[208:215], v[66:69], v182, v182 op_sel_hi:[0,0,0]
	v_mfma_scale_f32_16x16x128_f8f6f4 v[58:61], v[10:17], v[216:223], v[58:61], v182, v182 op_sel_hi:[0,0,0]
	s_setprio 0
	s_setprio 1
	v_mfma_scale_f32_16x16x128_f8f6f4 v[54:57], v[18:25], v[192:199], v[54:57], v182, v182 op_sel_hi:[0,0,0]
	v_mfma_scale_f32_16x16x128_f8f6f4 v[46:49], v[18:25], v[200:207], v[46:49], v182, v182 op_sel_hi:[0,0,0]
	v_mfma_scale_f32_16x16x128_f8f6f4 v[38:41], v[18:25], v[208:215], v[38:41], v182, v182 op_sel_hi:[0,0,0]
	v_mfma_scale_f32_16x16x128_f8f6f4 v[30:33], v[18:25], v[216:223], v[30:33], v182, v182 op_sel_hi:[0,0,0]
	v_mfma_scale_f32_16x16x128_f8f6f4 v[50:53], v[184:191], v[192:199], v[50:53], v182, v182 op_sel_hi:[0,0,0]
	v_mfma_scale_f32_16x16x128_f8f6f4 v[42:45], v[184:191], v[200:207], v[42:45], v182, v182 op_sel_hi:[0,0,0]
	v_mfma_scale_f32_16x16x128_f8f6f4 v[34:37], v[184:191], v[208:215], v[34:37], v182, v182 op_sel_hi:[0,0,0]
	v_mfma_scale_f32_16x16x128_f8f6f4 v[26:29], v[184:191], v[216:223], v[26:29], v182, v182 op_sel_hi:[0,0,0]
	s_setprio 0
	s_cmp_lg_u32 s98, 1
	s_cbranch_scc1 .Lhb_p5_3
	s_barrier

.Lhb_p5_4:
	s_setprio 1
	s_waitcnt lgkmcnt(0)
	v_mfma_scale_f32_16x16x128_f8f6f4 v[150:153], v[10:17], v[192:199], v[150:153], v182, v182 op_sel_hi:[0,0,0]
	v_mfma_scale_f32_16x16x128_f8f6f4 v[142:145], v[10:17], v[200:207], v[142:145], v182, v182 op_sel_hi:[0,0,0]
	v_mfma_scale_f32_16x16x128_f8f6f4 v[134:137], v[10:17], v[208:215], v[134:137], v182, v182 op_sel_hi:[0,0,0]
	v_mfma_scale_f32_16x16x128_f8f6f4 v[126:129], v[10:17], v[216:223], v[126:129], v182, v182 op_sel_hi:[0,0,0]
	v_mfma_scale_f32_16x16x128_f8f6f4 v[146:149], v[184:191], v[192:199], v[146:149], v182, v182 op_sel_hi:[0,0,0]
	v_mfma_scale_f32_16x16x128_f8f6f4 v[138:141], v[184:191], v[200:207], v[138:141], v182, v182 op_sel_hi:[0,0,0]
	v_mfma_scale_f32_16x16x128_f8f6f4 v[130:133], v[184:191], v[208:215], v[130:133], v182, v182 op_sel_hi:[0,0,0]
	v_mfma_scale_f32_16x16x128_f8f6f4 v[122:125], v[184:191], v[216:223], v[122:125], v182, v182 op_sel_hi:[0,0,0]
	s_setprio 0
	s_setprio 1
	v_mfma_scale_f32_16x16x128_f8f6f4 v[118:121], v[2:9], v[192:199], v[118:121], v182, v182 op_sel_hi:[0,0,0]
	v_mfma_scale_f32_16x16x128_f8f6f4 v[110:113], v[2:9], v[200:207], v[110:113], v182, v182 op_sel_hi:[0,0,0]
	v_mfma_scale_f32_16x16x128_f8f6f4 v[102:105], v[2:9], v[208:215], v[102:105], v182, v182 op_sel_hi:[0,0,0]
	v_mfma_scale_f32_16x16x128_f8f6f4 v[94:97], v[2:9], v[216:223], v[94:97], v182, v182 op_sel_hi:[0,0,0]
	v_mfma_scale_f32_16x16x128_f8f6f4 v[114:117], v[18:25], v[192:199], v[114:117], v182, v182 op_sel_hi:[0,0,0]
	v_mfma_scale_f32_16x16x128_f8f6f4 v[106:109], v[18:25], v[200:207], v[106:109], v182, v182 op_sel_hi:[0,0,0]
	v_mfma_scale_f32_16x16x128_f8f6f4 v[98:101], v[18:25], v[208:215], v[98:101], v182, v182 op_sel_hi:[0,0,0]
	v_mfma_scale_f32_16x16x128_f8f6f4 v[90:93], v[18:25], v[216:223], v[90:93], v182, v182 op_sel_hi:[0,0,0]
	s_setprio 0
	s_cmp_lg_u32 s98, 1
	s_cbranch_scc1 .Lhb_p5_5
	s_barrier

.Lhb_p5_6:
	s_setprio 1
	s_waitcnt lgkmcnt(0)
	v_mfma_scale_f32_16x16x128_f8f6f4 v[86:89], v[10:17], v[192:199], v[86:89], v182, v182 op_sel_hi:[0,0,0]
	v_mfma_scale_f32_16x16x128_f8f6f4 v[78:81], v[10:17], v[200:207], v[78:81], v182, v182 op_sel_hi:[0,0,0]
	v_mfma_scale_f32_16x16x128_f8f6f4 v[70:73], v[10:17], v[208:215], v[70:73], v182, v182 op_sel_hi:[0,0,0]
	v_mfma_scale_f32_16x16x128_f8f6f4 v[62:65], v[10:17], v[216:223], v[62:65], v182, v182 op_sel_hi:[0,0,0]
	v_mfma_scale_f32_16x16x128_f8f6f4 v[82:85], v[184:191], v[192:199], v[82:85], v182, v182 op_sel_hi:[0,0,0]
	v_mfma_scale_f32_16x16x128_f8f6f4 v[74:77], v[184:191], v[200:207], v[74:77], v182, v182 op_sel_hi:[0,0,0]
	v_mfma_scale_f32_16x16x128_f8f6f4 v[66:69], v[184:191], v[208:215], v[66:69], v182, v182 op_sel_hi:[0,0,0]
	v_mfma_scale_f32_16x16x128_f8f6f4 v[58:61], v[184:191], v[216:223], v[58:61], v182, v182 op_sel_hi:[0,0,0]
	s_setprio 0
	s_setprio 1
	v_mfma_scale_f32_16x16x128_f8f6f4 v[54:57], v[2:9], v[192:199], v[54:57], v182, v182 op_sel_hi:[0,0,0]
	v_mfma_scale_f32_16x16x128_f8f6f4 v[46:49], v[2:9], v[200:207], v[46:49], v182, v182 op_sel_hi:[0,0,0]
	v_mfma_scale_f32_16x16x128_f8f6f4 v[38:41], v[2:9], v[208:215], v[38:41], v182, v182 op_sel_hi:[0,0,0]
	v_mfma_scale_f32_16x16x128_f8f6f4 v[30:33], v[2:9], v[216:223], v[30:33], v182, v182 op_sel_hi:[0,0,0]
	v_mfma_scale_f32_16x16x128_f8f6f4 v[50:53], v[18:25], v[192:199], v[50:53], v182, v182 op_sel_hi:[0,0,0]
	v_mfma_scale_f32_16x16x128_f8f6f4 v[42:45], v[18:25], v[200:207], v[42:45], v182, v182 op_sel_hi:[0,0,0]
	v_mfma_scale_f32_16x16x128_f8f6f4 v[34:37], v[18:25], v[208:215], v[34:37], v182, v182 op_sel_hi:[0,0,0]
	v_mfma_scale_f32_16x16x128_f8f6f4 v[26:29], v[18:25], v[216:223], v[26:29], v182, v182 op_sel_hi:[0,0,0]
	s_setprio 0
	s_cmp_lg_u32 s98, 1
	s_cbranch_scc1 .Lhb_p5_7
	s_barrier

.Lhb_p7_0:
	s_setprio 1
	s_waitcnt lgkmcnt(0)
	v_mfma_scale_f32_16x16x128_f8f6f4 v[150:153], v[2:9], v[172:179], v[150:153], v182, v182 op_sel_hi:[0,0,0]
	v_mfma_scale_f32_16x16x128_f8f6f4 v[142:145], v[2:9], v[192:199], v[142:145], v182, v182 op_sel_hi:[0,0,0]
	v_mfma_scale_f32_16x16x128_f8f6f4 v[134:137], v[2:9], v[200:207], v[134:137], v182, v182 op_sel_hi:[0,0,0]
	v_mfma_scale_f32_16x16x128_f8f6f4 v[126:129], v[2:9], v[208:215], v[126:129], v182, v182 op_sel_hi:[0,0,0]
	v_mfma_scale_f32_16x16x128_f8f6f4 v[146:149], v[10:17], v[172:179], v[146:149], v182, v182 op_sel_hi:[0,0,0]
	v_mfma_scale_f32_16x16x128_f8f6f4 v[138:141], v[10:17], v[192:199], v[138:141], v182, v182 op_sel_hi:[0,0,0]
	v_mfma_scale_f32_16x16x128_f8f6f4 v[130:133], v[10:17], v[200:207], v[130:133], v182, v182 op_sel_hi:[0,0,0]
	v_mfma_scale_f32_16x16x128_f8f6f4 v[122:125], v[10:17], v[208:215], v[122:125], v182, v182 op_sel_hi:[0,0,0]
	s_setprio 0
	s_setprio 1
	v_mfma_scale_f32_16x16x128_f8f6f4 v[118:121], v[18:25], v[172:179], v[118:121], v182, v182 op_sel_hi:[0,0,0]
	v_mfma_scale_f32_16x16x128_f8f6f4 v[110:113], v[18:25], v[192:199], v[110:113], v182, v182 op_sel_hi:[0,0,0]
	v_mfma_scale_f32_16x16x128_f8f6f4 v[102:105], v[18:25], v[200:207], v[102:105], v182, v182 op_sel_hi:[0,0,0]
	v_mfma_scale_f32_16x16x128_f8f6f4 v[94:97], v[18:25], v[208:215], v[94:97], v182, v182 op_sel_hi:[0,0,0]
	v_mfma_scale_f32_16x16x128_f8f6f4 v[114:117], v[184:191], v[172:179], v[114:117], v182, v182 op_sel_hi:[0,0,0]
	v_mfma_scale_f32_16x16x128_f8f6f4 v[106:109], v[184:191], v[192:199], v[106:109], v182, v182 op_sel_hi:[0,0,0]
	v_mfma_scale_f32_16x16x128_f8f6f4 v[98:101], v[184:191], v[200:207], v[98:101], v182, v182 op_sel_hi:[0,0,0]
	v_mfma_scale_f32_16x16x128_f8f6f4 v[90:93], v[184:191], v[208:215], v[90:93], v182, v182 op_sel_hi:[0,0,0]
	s_setprio 0
	s_cmp_lg_u32 s98, 1
	s_cbranch_scc1 .Lhb_p7_1
	s_barrier
